# v103 + differential-attention key loop: loop-head scalar work rotated in front of the loop-back barrier, next-tile global loads issued after the K-fragment LDS reads
# speedup vs baseline: 1.0009x; 1.0009x over previous
.LBB0_554:
	s_sub_i32 s71, s71, 64
	s_addk_i32 s73, 0x4800
	s_add_i32 s72, s72, 1
	s_add_i32 s74, s74, 1
	s_add_i32 s4, s4, -1
	s_add_i32 s98, s71, 64
	s_cmp_gt_i32 s98, s75
	s_cselect_b32 s97, 1, 0
	s_bitcmp1_b32 s72, 0
	s_cselect_b32 s77, 0, 0x4400
	v_add_u32_e32 v96, s77, v235
	s_add_i32 s76, s4, 1
	s_cmp_gt_i32 s76, 0
	s_cselect_b64 s[40:41], -1, 0
	s_lshl_b32 s98, s4, 14
	s_add_u32 s92, s88, s98
	s_addc_u32 s93, s89, 0
	s_add_u32 s94, s90, s98
	s_addc_u32 s95, s91, 0
	s_mul_hi_u32 s76, s74, 0xaaaaaaab
	s_lshr_b32 s76, s76, 1
	s_cmpk_eq_i32 s71, 0xff80
	s_waitcnt lgkmcnt(0)
	s_barrier
	s_cbranch_scc1 .LBB0_572
	s_cmp_lg_u32 s97, 0
	s_cbranch_scc1 .LBB0_568
	s_branch .Ldf_rot_body
.LBB0_555:
	s_add_i32 s76, s4, 1
	s_cmp_gt_i32 s76, 0
	s_cselect_b64 s[40:41], -1, 0
	s_cmp_lt_i32 s76, 1
	s_cbranch_scc1 .LBB0_557
	s_lshl_b64 s[76:77], s[4:5], 14
	s_add_u32 s92, s88, s76
	s_addc_u32 s93, s89, s77
	s_add_u32 s94, s90, s76
	s_addc_u32 s95, s91, s77
.LBB0_557:
	s_add_i32 s76, s71, 64
	s_cmp_gt_i32 s76, s75
	s_cbranch_scc1 .LBB0_568
	s_mul_hi_u32 s76, s74, 0xaaaaaaab
	s_lshr_b32 s76, s76, 1
	s_bitcmp1_b32 s72, 0
	s_cselect_b32 s77, 0, 0x4400
	v_add_u32_e32 v96, s77, v235
.Ldf_rot_body:
	ds_read_b128 v[92:95], v96
	ds_read_b128 v[88:91], v96 offset:32
	ds_read_b128 v[84:87], v96 offset:64
	ds_read_b128 v[80:83], v96 offset:96
	ds_read_b128 v[120:123], v96 offset:8704
	ds_read_b128 v[116:119], v96 offset:8736
	ds_read_b128 v[112:115], v96 offset:8768
	ds_read_b128 v[208:211], v96 offset:8800
	s_andn2_b64 vcc, exec, s[40:41]
	s_cbranch_vccnz .Ldf_rot_nl0
	global_load_dwordx4 v[144:147], v246, s[92:93]
	global_load_dwordx4 v[148:151], v246, s[94:95]
	global_load_dwordx4 v[152:155], v245, s[92:93]
	global_load_dwordx4 v[156:159], v245, s[94:95]
.Ldf_rot_nl0:
	s_mul_i32 s76, s76, 0xd800
	s_sub_i32 s86, s73, s76
	s_andn2_b64 vcc, exec, s[42:43]
	v_add_u32_e32 v247, s86, v248
	s_cbranch_vccnz .LBB0_560
	ds_read_b128 v[184:187], v247 offset:32
	ds_read_b128 v[180:183], v247 offset:64
	ds_read_b128 v[188:191], v247
	ds_read_b128 v[176:179], v247 offset:96

.LBB0_568:
	s_andn2_b64 vcc, exec, s[40:41]
	s_cbranch_vccnz .Ldf_rot_nl1
	global_load_dwordx4 v[144:147], v246, s[92:93]
	global_load_dwordx4 v[148:151], v246, s[94:95]
	global_load_dwordx4 v[152:155], v245, s[92:93]
	global_load_dwordx4 v[156:159], v245, s[94:95]
